# conversion engine: stagger by workgroup ((blockIdx>>3)&3) instead of by wave
# speedup vs baseline: 1.0039x; 1.0025x over previous
; #define PG8_STAGE(bufoff, gbase, voff) do { _Pragma("unroll") for (int _i = 0; _i < 2; ++_i) \
;         __builtin_amdgcn_global_load_lds((const unsigned*)((const char*)(gbase) + (voff)[_i]), (PG8_LAS unsigned*)(lds + (bufoff) + ldsw + _i * 8192), 16, 0, 0); } while (0)
; #define PG8_WAIT_V(n) asm volatile("s_waitcnt vmcnt(" #n ")" ::: "memory")
; #define PG8_BAR __builtin_amdgcn_s_barrier()
; template <class Epi, class Sched, bool ALIGN_EPI = false, bool SP2 = false>
; __device__ __forceinline__ void gemm_phase(PG8_LAS unsigned char* lds, const Gemm g, const Sched& S, const Epi& E) {
;     const int tid = threadIdx.x, wid = __builtin_amdgcn_readfirstlane(tid >> 6), lane = tid & 63, wr = wid >> 2, wc = wid & 3, fr = lane & 15, fq = lane >> 4;
;     const int K = g.K, nt = K / BK;
;     unsigned voffA[2], voffB[2];
; #pragma unroll
;     for (int i = 0; i < 2; ++i) { int R, C; stage_rc(tid * 16 + i * 8192, R, C); const int Rb = Epi::PERM ? ((R & ~31) + perm32(R & 31)) : R;
;         voffA[i] = (unsigned)(R * g.lda + C) * 2u; voffB[i] = (unsigned)(Rb * g.ldb + C) * 2u; }
;     const size_t kstep = (size_t)(BK * 2);
;     const size_t hstepA = (size_t)HALF * g.lda * 2, hstepB = (size_t)HALF * g.ldb * 2;
;     const size_t tstepA = 2 * hstepA, tstepB = 2 * hstepB;
;     const unsigned ldsw = (unsigned)wid * 1024u;
;     const int aoff = lds_byte(wr * 64 + fr, fq * 8), boff = lds_byte(wc * 32 + fr, fq * 8);
;     ...
;         PG8_STAGE(PG8_SB(1, 0), cB + kstep, voffB); PG8_STAGE(PG8_SA(1, 0), cA + kstep, voffA); PG8_STAGE(PG8_SB(1, 1), cB + hstepB + kstep, voffB);
;         PG8_WAIT_V(6); PG8_BAR;
.LBB0_137:
	s_lshl_b32 s5, s5, 5
	s_mov_b64 s[18:19], 0x80
	s_and_b32 s5, s5, 0x60
	s_add_i32 m0, s55, 0x18000
	v_lshl_add_u64 v[8:9], v[8:9], 0, s[18:19]
	s_lshl_b32 s1, s4, 13
	s_lshl_b32 s22, s5, 7
	s_waitcnt vmcnt(2)
	s_barrier
	global_load_lds_dwordx4 v[8:9], off
	v_lshl_add_u64 v[4:5], v[4:5], 0, s[18:19]
	s_add_i32 m0, s55, 0x1a000
	s_add_i32 s75, s55, 0x8000
	s_add_i32 s76, s55, 0xa000
	global_load_lds_dwordx4 v[4:5], off
	v_lshl_add_u64 v[2:3], v[2:3], 0, s[18:19]
	s_mov_b32 m0, s75
	s_add_u32 s20, s8, 0x100080
	global_load_lds_dwordx4 v[2:3], off
	v_lshl_add_u64 v[2:3], v[6:7], 0, s[18:19]
	s_mov_b32 m0, s76
	s_addc_u32 s21, s9, 0
	global_load_lds_dwordx4 v[2:3], off
	s_add_i32 m0, s55, 0x1c000
	v_lshl_add_u64 v[2:3], s[20:21], 0, v[140:141]
	global_load_lds_dwordx4 v[2:3], off
	v_lshl_add_u64 v[2:3], s[20:21], 0, v[144:145]
	s_add_i32 m0, s55, 0x1e000
	v_and_b32_e32 v4, 32, v162
	global_load_lds_dwordx4 v[2:3], off
	v_and_b32_e32 v2, 15, v0
	v_lshlrev_b32_e32 v3, 1, v14
	v_lshl_or_b32 v163, s4, 6, v2
	v_lshl_or_b32 v2, v2, 6, v3
	v_bitop3_b32 v2, v2, s1, v4 bitop3:0xde
	v_lshlrev_b32_e32 v5, 6, v0
	s_movk_i32 s1, 0x3c0
	v_and_or_b32 v3, v5, s1, v3
	v_bitop3_b32 v164, s22, v3, v4 bitop3:0xf6
	v_lshlrev_b32_e32 v3, 10, v0
	v_and_b32_e32 v3, 0x60000, v3
	v_lshlrev_b32_e32 v4, 13, v12
	v_or3_b32 v3, v10, v3, v4
	s_cmpk_lt_u32 s14, 0x100
	v_add_u32_e32 v148, v3, v11
	v_lshlrev_b32_e32 v3, 6, v13
	s_waitcnt vmcnt(6)
	s_cselect_b64 s[20:21], -1, 0
	s_add_u32 s22, s62, 0x2000
	v_and_b32_e32 v3, 0xe0000, v3
	v_or_b32_e32 v165, s5, v14
	s_addc_u32 s23, s63, 0
	v_or3_b32 v3, v10, v3, v4
	s_add_i32 s83, 0, 0x10000
	s_add_i32 s89, 0, 0x14000
	v_or_b32_e32 v166, 0xffffec00, v165
	s_ashr_i32 s77, s74, 31
	s_ashr_i32 s81, s2, 31
	v_mov_b32_e32 v149, v147
	v_add_u32_e32 v150, v3, v11
	v_mov_b32_e32 v151, v147
	v_mov_b64_e32 v[152:153], 0x900
	v_mov_b64_e32 v[154:155], 0x8ff
	v_add_u32_e32 v167, s83, v164
	v_add_u32_e32 v168, s89, v164
	v_add_u32_e32 v169, 0, v2
	s_mov_b32 s90, 0xc2a00000
	s_mov_b32 s91, 0xc1f00000
	v_mov_b32_e32 v170, 0x42a00000
	v_mov_b32_e32 v171, 0x41f00000
	s_mov_b32 s92, 0
	s_barrier
	s_bfe_u32 s32, s2, 0x20003
	s_sub_i32 s32, 0, s32
	s_mov_b32 s97, 0
	v_readlane_b32 s98, v244, 0
	v_readlane_b32 s99, v244, 1
	s_nop 3
	s_sub_u32 s98, s98, 0x98
	s_subb_u32 s99, s99, 0
	s_load_dwordx2 s[100:101], s[98:99], 0x58
	s_waitcnt lgkmcnt(0)
	v_writelane_b32 v245, s100, 0
	v_writelane_b32 v245, s101, 1
	s_nop 1
	s_load_dwordx2 s[100:101], s[98:99], 0x60
	s_waitcnt lgkmcnt(0)
	v_writelane_b32 v245, s100, 2
	v_writelane_b32 v245, s101, 3
	s_nop 1
	s_load_dwordx2 s[100:101], s[98:99], 0x50
	s_waitcnt lgkmcnt(0)
	v_writelane_b32 v245, s100, 4
	v_writelane_b32 v245, s101, 5
	s_nop 1
	s_load_dwordx2 s[100:101], s[98:99], 0x38
	s_waitcnt lgkmcnt(0)
	v_writelane_b32 v245, s100, 6
	v_writelane_b32 v245, s101, 7
	s_nop 1
	s_load_dwordx2 s[100:101], s[98:99], 0x40
	s_waitcnt lgkmcnt(0)
	v_writelane_b32 v245, s100, 8
	v_writelane_b32 v245, s101, 9
	s_nop 1
	s_load_dwordx2 s[100:101], s[98:99], 0x48
	s_waitcnt lgkmcnt(0)
	v_writelane_b32 v245, s100, 10
	v_writelane_b32 v245, s101, 11
	s_mul_hi_u32 s93, s80, 0xbe82fa0c
	s_lshr_b32 s93, s93, 8
	s_mul_i32 s85, s93, 0x158
	s_sub_i32 s85, s80, s85
	s_lshl_b32 s93, s93, 16
	s_or_b32 s85, s85, s93
	s_mov_b64 s[100:101], 0
	s_branch .LBB0_140
